# lean4 + one static s_setprio 1 for waves 4-7 during the attention rounds (reset at kind4 exit)
# baseline (speedup 1.0000x reference)
; __global__ void __launch_bounds__(NTHR, 2) trunk_fwd(Args args) {
;     ...
;             unsigned char* wsg = rd_ptr_generic(24);
;             const int rounds = (512 + G - 1) / G;
;             for (int r = 0; r < rounds; ++r) {
;                 const int p = (r & 1) ? (G - 1 - bx) : bx; const int u = r * G + p;
;                 if (u < 512) { const int qb = 15 - (u >> 5), pair = u & 31, bl = pair >> 3, j = pair & 7;
.LBB0_1009:
	s_or_b64 exec, exec, s[0:1]
	v_readfirstlane_b32 s0, v230
	s_cmpk_lt_u32 s0, 0x100
	s_cbranch_scc1 .Lk4_noprio
	s_setprio 1
.Lk4_noprio:
	s_add_i32 s0, s60, 0x1ff
	s_ashr_i32 s1, s0, 31
	s_abs_i32 s0, s0
	s_mul_hi_u32 s2, s0, s18
	s_mul_i32 s3, s2, s16
	s_sub_i32 s0, s0, s3
	s_xor_b32 s1, s1, s17
	s_add_i32 s3, s2, 1
	s_sub_i32 s4, s0, s16
	s_cmp_ge_u32 s0, s16
	s_waitcnt lgkmcnt(0)
	s_barrier
	s_cselect_b32 s2, s3, s2
	ds_read_b64 v[0:1], v231
	s_cselect_b32 s0, s4, s0
	s_add_i32 s3, s2, 1
	s_cmp_ge_u32 s0, s16
	s_cselect_b32 s0, s3, s2
	s_xor_b32 s0, s0, s1
	s_sub_i32 s18, s0, s1
	s_waitcnt lgkmcnt(0)
	v_readfirstlane_b32 s5, v1
	s_cmp_lt_i32 s18, 1
	v_readfirstlane_b32 s4, v0
	s_cbranch_scc1 .LBB0_1092
	s_not_b32 s0, s58
	s_add_i32 s19, s60, s0
	s_add_u32 s20, s4, 0x17400000
	s_addc_u32 s21, s5, 0
	s_add_u32 s22, s4, 0x18400000
	s_addc_u32 s23, s5, 0
	s_add_u32 s59, s4, 0x19400000
	s_addc_u32 s61, s5, 0
	s_add_u32 s66, s4, 0x15400000
	s_addc_u32 s67, s5, 0
	s_mov_b32 s68, 0
	s_mov_b32 s69, 0
	s_mov_b32 s70, 0
	s_branch .LBB0_1013

; #define LAS __attribute__((address_space(3)))
; __device__ __forceinline__ unsigned xb_xcc_id() { return (unsigned)__builtin_amdgcn_s_getreg((3 << 11) | 20) & 0xFu; }
; #define P_WS() (rd_ptr(24))
; __global__ void __launch_bounds__(NTHR, 2) trunk_fwd(Args args) {
;     ...
;             }
;         } else if (kind == 5 && !SK5) {
;     ...
;         { XcdBarrier bar; bar.bar = (unsigned*)(P_WS() + WS_BAR); bar.x = xb_xcc_id(); bar.st = (volatile LAS unsigned*)(lds + MISC_OFF); xcd_barrier(bar); }
.LBB0_1092:
	s_setprio 0
	s_mov_b64 s[0:1], 0
